# skip the grid barrier after the final PEER phase (st=38): nothing follows it
# speedup vs baseline: 1.0045x; 1.0045x over previous
; __global__ void __launch_bounds__(NTHR, 2) mega(P p) {
;     ...
;   for (int st = -1; st < 40; st++) {
;     const int l = st < 0 ? 0 : st / 10;
;     const int ph = st < 0 ? -1 : st - l * 10;
;     const int need_ctx = l < 3;
;     const int nrows = need_ctx ? T_ALL : T_LAT;
;     ...
;     if (ph != 9) xcd_barrier(xb);
.LBB0_1510:
	s_and_b64 vcc, exec, s[0:1]
	v_readlane_b32 s0, v254, 23
	v_readlane_b32 s1, v254, 24
	s_cbranch_vccz .LBB0_1512
	v_readlane_b32 s0, v254, 22
	v_readlane_b32 s1, v254, 21
	s_cmp_eq_u32 s1, 38
	s_cselect_b32 s0, 9, s0
	s_cmp_lg_u32 s0, 9
	s_cselect_b64 s[0:1], -1, 0
